# issue the K/V LDS-DMA pieces after the QK MFMAs instead of at the tile top
# speedup vs baseline: 1.0425x; 1.0113x over previous
; __device__ void item_attn(PP p, int qb, int b, int hh, u16* lds) {
;     ...
;   for (int kt = 0; kt < ntiles; kt += 2) {
;     if (kt + 2 < ntiles) as_load(B, kg, vg, kt + 2);
;     attn_tile(lds, qa, oa0, oa1, lacc, ma, mz, r, h, kt == 0);
.LBB0_456:
	s_add_u32 s60, s46, 0x6000
	s_addc_u32 s61, s47, 0
	s_add_u32 m0, s62, 35840
	s_nop 0
	global_load_lds_dwordx4 v213, s[60:61]
	s_add_u32 s60, s60, 0x1000
	s_addc_u32 s61, s61, 0
	s_add_u32 m0, s62, 39936
	s_nop 0
	global_load_lds_dwordx4 v213, s[60:61]
	s_add_i32 s58, s45, -1
	s_cmp_lt_i32 s58, s44
	s_cselect_b64 s[0:1], -1, 0
	s_cmp_ge_i32 s58, s44
	s_cbranch_scc1 .LBB0_458

; __device__ __forceinline__ void attn_tile(const u16* sb, const bf16x8 (&qa)[6], f32x16& o0, f32x16& o1, f32x16& lacc,
;                                           float& m, bool& mz, int r, int h, bool first) {
;     ...
;   float mxa = max3f(s0[0], s0[1], s0[2]), mxb = max3f(s0[3], s0[4], s0[5]);
;   float mxc = max3f(s0[6], s0[7], s0[8]), mxd = max3f(s0[9], s0[10], s0[11]);
;   mxa = max3f(mxa, s0[12], s0[13]); mxb = max3f(mxb, s0[14], s0[15]);
;   mxc = max3f(mxc, s1[0], s1[1]); mxd = max3f(mxd, s1[2], s1[3]);
;   mxa = max3f(mxa, s1[4], s1[5]); mxb = max3f(mxb, s1[6], s1[7]);
;   mxc = max3f(mxc, s1[8], s1[9]); mxd = max3f(mxd, s1[10], s1[11]);
;   mxa = max3f(mxa, s1[12], s1[13]); mxb = max3f(mxb, s1[14], s1[15]);
;   const float lm = max3f(mxa, mxb, fmaxf(mxc, mxd));
;   bool slow;
;   if (first) {
;     const float mx = fmaxf(lm, __shfl_xor(lm, 32));
;     slow = __any(mx > 30.f || mx < -30.f);
;   } else {
;     slow = __any(lm > 30.f);
;   }
;   if (slow) {
;     const float mx = fmaxf(lm, __shfl_xor(lm, 32));
;     const float d = first ? mx : fmaxf(mx, 0.f);
;     const float alpha = first ? 1.f : __builtin_amdgcn_exp2f(-d);
;     m += d;
;     mz = false;
; #pragma unroll
;     for (int i = 0; i < 16; ++i) { s0[i] -= d; s1[i] -= d; o0[i] *= alpha; o1[i] *= alpha; }
;     lacc[0] *= alpha;
;   }
;   float pa = 0.f, pb = 0.f, pc = 0.f, pd = 0.f;
; #pragma unroll
;   for (int i = 0; i < 16; ++i) {
;     s0[i] = __builtin_amdgcn_exp2f(s0[i]); s1[i] = __builtin_amdgcn_exp2f(s1[i]);
;     if ((i & 3) == 0) pa += s0[i] + s1[i];
;     else if ((i & 3) == 1) pb += s0[i] + s1[i];
;     else if ((i & 3) == 2) pc += s0[i] + s1[i];
;     else pd += s0[i] + s1[i];
;   }
;   lacc[0] += (pa + pb) + (pc + pd);
;   const u16* vp = sb + 64 * KLD + r * VLD + 8 * h;
;   __builtin_amdgcn_s_setprio(1);
; #pragma unroll
;   for (int kb = 0; kb < 2; ++kb) {
; #pragma unroll
;     for (int s = 0; s < 2; ++s) {
;       const bf16x8 pf = pack_p(kb == 0 ? s0 : s1, 8 * s);
;       const int koff = kb * 32 + 16 * s;
;       const bf16x8 v0 = *(const bf16x8*)(vp + koff);
;       const bf16x8 v1 = *(const bf16x8*)(vp + 32 * VLD + koff);
;       o0 = mfma32(v0, pf, o0);
;       o1 = mfma32(v1, pf, o1);
;     }
;   }
;   __builtin_amdgcn_s_setprio(0);
; __device__ void item_attn(PP p, int qb, int b, int hh, u16* lds) {
;     ...
;     if (kt + 2 < ntiles) as_load(B, kg, vg, kt + 2);
.Lqkd_e:
	s_add_u32 s60, s42, 0x9000
	s_addc_u32 s61, s43, 0
	s_add_u32 m0, s62, 22528
	s_nop 0
	global_load_lds_dwordx4 v96, s[60:61]
	s_add_u32 m0, s62, 26624
	s_nop 0
	global_load_lds_dwordx4 v97, s[60:61]
	s_add_u32 m0, s62, 30720
	s_nop 0
	global_load_lds_dwordx4 v106, s[60:61]
	s_add_u32 s60, s46, 0x6000
	s_addc_u32 s61, s47, 0
	s_add_u32 m0, s62, 35840
	s_nop 0
	global_load_lds_dwordx4 v213, s[60:61]
	s_add_u32 s60, s60, 0x1000
	s_addc_u32 s61, s61, 0
	s_add_u32 m0, s62, 39936
	s_nop 0
	global_load_lds_dwordx4 v213, s[60:61]
	ds_read_b128 v[214:217], v164 offset:13312
	ds_read_b128 v[218:221], v164 offset:17408
	ds_read_b128 v[222:225], v255 offset:13312
	ds_read_b128 v[226:229], v255 offset:17408
	ds_read_b128 v[230:233], v163 offset:13312
	ds_read_b128 v[234:237], v163 offset:17408
	ds_read_b128 v[238:241], v254 offset:13312
	ds_read_b128 v[242:245], v254 offset:17408
	s_nop 1
	s_setprio 0
	v_max3_f32 v142, v50, v51, v52
	v_max3_f32 v144, v56, v57, v58
	v_max3_f32 v145, v59, v60, v61
	v_max3_f32 v143, v53, v54, v55
	v_max3_f32 v142, v142, v62, v63
	v_max3_f32 v144, v144, v34, v35
	v_max3_f32 v145, v145, v36, v37
	v_max3_f32 v143, v143, v64, v65
	v_max3_f32 v142, v142, v38, v39
	v_max3_f32 v144, v144, v42, v43
	v_max3_f32 v145, v145, v44, v45
	v_max3_f32 v143, v143, v40, v41
	v_max3_f32 v142, v142, v46, v47
	v_max_f32_e32 v145, v145, v145
	v_max_f32_e32 v144, v144, v144
	v_max3_f32 v143, v143, v48, v49
	v_max_f32_e32 v144, v144, v145
	v_max3_f32 v142, v142, v143, v144
	v_cmp_lt_f32_e32 vcc, s5, v142
	s_cbranch_vccz .LBB0_464
	ds_bpermute_b32 v143, v161, v142
	s_andn2_b64 s[48:49], s[48:49], exec
	s_waitcnt lgkmcnt(0)
	v_max3_f32 v142, v142, v143, 0
	v_exp_f32_e64 v144, -v142
	v_add_f32_e32 v162, v162, v142
	v_pk_add_f32 v[50:51], v[50:51], v[142:143] op_sel_hi:[1,0] neg_lo:[0,1] neg_hi:[0,1]
	v_pk_add_f32 v[34:35], v[34:35], v[142:143] op_sel_hi:[1,0] neg_lo:[0,1] neg_hi:[0,1]
	v_pk_add_f32 v[52:53], v[52:53], v[142:143] op_sel_hi:[1,0] neg_lo:[0,1] neg_hi:[0,1]
	v_pk_add_f32 v[36:37], v[36:37], v[142:143] op_sel_hi:[1,0] neg_lo:[0,1] neg_hi:[0,1]
	v_pk_add_f32 v[54:55], v[54:55], v[142:143] op_sel_hi:[1,0] neg_lo:[0,1] neg_hi:[0,1]
	v_pk_add_f32 v[38:39], v[38:39], v[142:143] op_sel_hi:[1,0] neg_lo:[0,1] neg_hi:[0,1]
	v_pk_add_f32 v[56:57], v[56:57], v[142:143] op_sel_hi:[1,0] neg_lo:[0,1] neg_hi:[0,1]
	v_pk_add_f32 v[40:41], v[40:41], v[142:143] op_sel_hi:[1,0] neg_lo:[0,1] neg_hi:[0,1]
	v_pk_add_f32 v[58:59], v[58:59], v[142:143] op_sel_hi:[1,0] neg_lo:[0,1] neg_hi:[0,1]
	v_pk_add_f32 v[42:43], v[42:43], v[142:143] op_sel_hi:[1,0] neg_lo:[0,1] neg_hi:[0,1]
	v_pk_add_f32 v[60:61], v[60:61], v[142:143] op_sel_hi:[1,0] neg_lo:[0,1] neg_hi:[0,1]
	v_pk_add_f32 v[44:45], v[44:45], v[142:143] op_sel_hi:[1,0] neg_lo:[0,1] neg_hi:[0,1]
	v_pk_add_f32 v[62:63], v[62:63], v[142:143] op_sel_hi:[1,0] neg_lo:[0,1] neg_hi:[0,1]
	v_pk_add_f32 v[46:47], v[46:47], v[142:143] op_sel_hi:[1,0] neg_lo:[0,1] neg_hi:[0,1]
	v_pk_add_f32 v[64:65], v[64:65], v[142:143] op_sel_hi:[1,0] neg_lo:[0,1] neg_hi:[0,1]
	v_pk_add_f32 v[48:49], v[48:49], v[142:143] op_sel_hi:[1,0] neg_lo:[0,1] neg_hi:[0,1]
	v_pk_mul_f32 v[32:33], v[32:33], v[144:145] op_sel_hi:[1,0]
	v_pk_mul_f32 v[30:31], v[30:31], v[144:145] op_sel_hi:[1,0]
	v_pk_mul_f32 v[28:29], v[28:29], v[144:145] op_sel_hi:[1,0]
	v_pk_mul_f32 v[26:27], v[26:27], v[144:145] op_sel_hi:[1,0]
	v_pk_mul_f32 v[24:25], v[24:25], v[144:145] op_sel_hi:[1,0]
	v_pk_mul_f32 v[22:23], v[22:23], v[144:145] op_sel_hi:[1,0]
	v_pk_mul_f32 v[20:21], v[20:21], v[144:145] op_sel_hi:[1,0]
	v_pk_mul_f32 v[18:19], v[18:19], v[144:145] op_sel_hi:[1,0]
	v_pk_mul_f32 v[16:17], v[16:17], v[144:145] op_sel_hi:[1,0]
	v_pk_mul_f32 v[14:15], v[14:15], v[144:145] op_sel_hi:[1,0]
	v_pk_mul_f32 v[12:13], v[12:13], v[144:145] op_sel_hi:[1,0]
	v_pk_mul_f32 v[10:11], v[10:11], v[144:145] op_sel_hi:[1,0]
	v_pk_mul_f32 v[8:9], v[8:9], v[144:145] op_sel_hi:[1,0]
	v_pk_mul_f32 v[6:7], v[6:7], v[144:145] op_sel_hi:[1,0]
	v_pk_mul_f32 v[4:5], v[4:5], v[144:145] op_sel_hi:[1,0]
	v_pk_mul_f32 v[2:3], v[2:3], v[144:145] op_sel_hi:[1,0]
	v_mul_f32_e32 v136, v136, v144
.LBB0_464:
	v_exp_f32_e32 v147, v53
	v_exp_f32_e32 v149, v37
	v_exp_f32_e32 v145, v57
	v_exp_f32_e32 v53, v41
	v_exp_f32_e32 v143, v61
	v_exp_f32_e32 v45, v45
	v_exp_f32_e32 v37, v65
	v_exp_f32_e32 v41, v49
	v_exp_f32_e32 v146, v34
	v_exp_f32_e32 v152, v35
	v_exp_f32_e32 v153, v36
	v_exp_f32_e32 v144, v38
	v_exp_f32_e32 v150, v39
	v_exp_f32_e32 v151, v40
	v_exp_f32_e32 v142, v42
	v_exp_f32_e32 v38, v43
	v_exp_f32_e32 v39, v44
	v_exp_f32_e32 v36, v46
	v_exp_f32_e32 v34, v47
	v_exp_f32_e32 v35, v48
	v_exp_f32_e32 v148, v50
	v_exp_f32_e32 v50, v51
	v_exp_f32_e32 v51, v52
	v_exp_f32_e32 v52, v54
	v_exp_f32_e32 v48, v55
	v_exp_f32_e32 v49, v56
	v_exp_f32_e32 v44, v58
	v_exp_f32_e32 v46, v59
	v_exp_f32_e32 v47, v60
	v_exp_f32_e32 v40, v62
	v_exp_f32_e32 v42, v63
	v_exp_f32_e32 v43, v64
	s_setprio 1
	v_cvt_pk_bf16_f32 v58, v148, v50
	v_cvt_pk_bf16_f32 v59, v51, v147
	v_cvt_pk_bf16_f32 v60, v52, v48
	v_cvt_pk_bf16_f32 v61, v49, v145
	v_cvt_pk_bf16_f32 v246, v44, v46
	v_cvt_pk_bf16_f32 v247, v47, v143
	v_cvt_pk_bf16_f32 v248, v40, v42
	v_cvt_pk_bf16_f32 v249, v43, v37
	s_waitcnt lgkmcnt(0)
	v_mfma_f32_32x32x16_bf16 v[18:33], v[214:217], v[58:61], v[18:33]
	v_mfma_f32_32x32x16_bf16 v[2:17], v[218:221], v[58:61], v[2:17]
	v_cvt_pk_bf16_f32 v58, v146, v152
	v_cvt_pk_bf16_f32 v59, v153, v149
	v_cvt_pk_bf16_f32 v60, v144, v150
	v_cvt_pk_bf16_f32 v61, v151, v53
	v_mfma_f32_32x32x16_bf16 v[18:33], v[222:225], v[246:249], v[18:33]
	v_mfma_f32_32x32x16_bf16 v[2:17], v[226:229], v[246:249], v[2:17]
	v_cvt_pk_bf16_f32 v246, v142, v38
	v_cvt_pk_bf16_f32 v247, v39, v45
	v_cvt_pk_bf16_f32 v248, v36, v34
	v_cvt_pk_bf16_f32 v249, v35, v41
	v_mfma_f32_32x32x16_bf16 v[18:33], v[230:233], v[58:61], v[18:33]
	v_mfma_f32_32x32x16_bf16 v[2:17], v[234:237], v[58:61], v[2:17]
	v_mfma_f32_32x32x16_bf16 v[18:33], v[238:241], v[246:249], v[18:33]
	v_mfma_f32_32x32x16_bf16 v[2:17], v[242:245], v[246:249], v[2:17]
	s_setprio 0
	s_waitcnt vmcnt(0)
	s_cmp_ge_i32 s45, s44
	s_waitcnt lgkmcnt(0)
	s_barrier
	s_cbranch_scc1 .LBB0_466
; __device__ __forceinline__ void attn_tile(const u16* sb, const bf16x8 (&qa)[6], f32x16& o0, f32x16& o1, f32x16& lacc,
;                                           float& m, bool& mz, int r, int h, bool first) {
;   const u16* kp = sb + r * KLD + h * 8;
;   f32x16 s0, s1;
;   __builtin_amdgcn_s_setprio(1);
;   if (mz) {
; #pragma unroll
;     for (int i = 0; i < 16; ++i) { s0[i] = 0.f; s1[i] = 0.f; }
;     attn_qk(kp, qa, s0, s1);
;   } else {
; #pragma unroll
;     for (int i = 0; i < 16; ++i) { s0[i] = -m; s1[i] = -m; }
;     attn_qk(kp, qa, s0, s1);
;   }
; __device__ void item_attn(PP p, int qb, int b, int hh, u16* lds) {
;     ...
;     as_store(A, lds + ATT_STAGE, kl0, kl1, kl2, vl);
;     __syncthreads();
;     if (kt + 3 < ntiles) as_load(A, kg, vg, kt + 3);
.LBB0_466:
	v_pk_add_f32 v[50:51], v[50:51], v[152:153]
	v_pk_add_f32 v[48:49], v[48:49], v[150:151]
	v_pk_add_f32 v[38:39], v[46:47], v[38:39]
	v_pk_add_f32 v[48:49], v[48:49], v[50:51]
	v_pk_add_f32 v[34:35], v[42:43], v[34:35]
	v_pk_add_f32 v[38:39], v[38:39], v[48:49]
	v_pk_add_f32 v[42:43], v[52:53], v[144:145]
	v_pk_add_f32 v[34:35], v[34:35], v[38:39]
	v_pk_add_f32 v[38:39], v[148:149], v[146:147]
	v_pk_add_f32 v[36:37], v[40:41], v[36:37]
	v_cmp_lt_i32_e32 vcc, s45, v165
	v_pk_add_f32 v[38:39], v[42:43], v[38:39]
	v_pk_add_f32 v[42:43], v[44:45], v[142:143]
	s_nop 0
	v_pk_add_f32 v[38:39], v[42:43], v[38:39]
	s_nop 0
	v_pk_add_f32 v[36:37], v[36:37], v[38:39]
	s_nop 0
	v_pk_add_f32 v[34:35], v[34:35], v[36:37]
	s_nop 0
	v_add_f32_e32 v34, v34, v35
	v_add_f32_e32 v136, v136, v34
	s_and_saveexec_b64 s[40:41], vcc
	s_cbranch_execz .LBB0_475
	ds_read_b128 v[214:217], v90 offset:22528
	ds_read_b128 v[218:221], v90 offset:28672
	ds_read_b128 v[222:225], v91 offset:22528
	ds_read_b128 v[226:229], v91 offset:28672
	ds_read_b128 v[230:233], v92 offset:22528
	ds_read_b128 v[234:237], v92 offset:28672
	ds_read_b128 v[238:241], v93 offset:22528
	ds_read_b128 v[242:245], v93 offset:28672
	ds_read_b128 v[246:249], v94 offset:22528
	ds_read_b128 v[250:253], v94 offset:28672
	ds_read_b128 v[142:145], v95 offset:22528
	ds_read_b128 v[146:149], v95 offset:28672
	s_setprio 1
	s_cmp_lg_u64 s[48:49], 0
	s_cbranch_scc1 .Lmz_o
	v_xor_b32_e32 v34, 0x80000000, v162
	v_mov_b32_e32 v35, v34
	v_mov_b32_e32 v36, v34
	v_mov_b32_e32 v37, v34
	v_mov_b32_e32 v38, v34
	v_mov_b32_e32 v39, v34
	v_mov_b32_e32 v40, v34
	v_mov_b32_e32 v41, v34
	v_mov_b32_e32 v42, v34
	v_mov_b32_e32 v43, v34
	v_mov_b32_e32 v44, v34
	v_mov_b32_e32 v45, v34
	v_mov_b32_e32 v46, v34
	v_mov_b32_e32 v47, v34
	v_mov_b32_e32 v48, v34
	v_mov_b32_e32 v49, v34
	s_waitcnt lgkmcnt(8)
	s_nop 0
	v_mfma_f32_32x32x16_bf16 v[50:65], v[214:217], v[66:69], v[34:49]
	v_mfma_f32_32x32x16_bf16 v[34:49], v[218:221], v[66:69], v[34:49]
	v_mfma_f32_32x32x16_bf16 v[50:65], v[222:225], v[70:73], v[50:65]
	v_mfma_f32_32x32x16_bf16 v[34:49], v[226:229], v[70:73], v[34:49]
	s_waitcnt lgkmcnt(4)
	v_mfma_f32_32x32x16_bf16 v[50:65], v[230:233], v[74:77], v[50:65]
	v_mfma_f32_32x32x16_bf16 v[34:49], v[234:237], v[74:77], v[34:49]
	v_mfma_f32_32x32x16_bf16 v[50:65], v[238:241], v[78:81], v[50:65]
	v_mfma_f32_32x32x16_bf16 v[34:49], v[242:245], v[78:81], v[34:49]
	s_waitcnt lgkmcnt(0)
	v_mfma_f32_32x32x16_bf16 v[50:65], v[246:249], v[82:85], v[50:65]
	v_mfma_f32_32x32x16_bf16 v[34:49], v[250:253], v[82:85], v[34:49]
	v_mfma_f32_32x32x16_bf16 v[50:65], v[142:145], v[86:89], v[50:65]
	v_mfma_f32_32x32x16_bf16 v[34:49], v[146:149], v[86:89], v[34:49]
	s_branch .Lqkd_o
.Lmz_o:
	s_waitcnt lgkmcnt(8)
	v_mfma_f32_32x32x16_bf16 v[50:65], v[214:217], v[66:69], 0
	v_mfma_f32_32x32x16_bf16 v[34:49], v[218:221], v[66:69], 0
	v_mfma_f32_32x32x16_bf16 v[50:65], v[222:225], v[70:73], v[50:65]
	v_mfma_f32_32x32x16_bf16 v[34:49], v[226:229], v[70:73], v[34:49]
	s_waitcnt lgkmcnt(4)
	v_mfma_f32_32x32x16_bf16 v[50:65], v[230:233], v[74:77], v[50:65]
	v_mfma_f32_32x32x16_bf16 v[34:49], v[234:237], v[74:77], v[34:49]
	v_mfma_f32_32x32x16_bf16 v[50:65], v[238:241], v[78:81], v[50:65]
	v_mfma_f32_32x32x16_bf16 v[34:49], v[242:245], v[78:81], v[34:49]
	s_waitcnt lgkmcnt(0)
	v_mfma_f32_32x32x16_bf16 v[50:65], v[246:249], v[82:85], v[50:65]
	v_mfma_f32_32x32x16_bf16 v[34:49], v[250:253], v[82:85], v[34:49]
	v_mfma_f32_32x32x16_bf16 v[50:65], v[142:145], v[86:89], v[50:65]
	v_mfma_f32_32x32x16_bf16 v[34:49], v[146:149], v[86:89], v[34:49]
.Lqkd_o:
	s_cmp_eq_u64 s[0:1], 0
	s_cbranch_scc1 .Lvd_skip
	s_add_u32 s60, s42, 0xc000
	s_addc_u32 s61, s43, 0
	s_add_u32 m0, s62, 0
	s_nop 0
	global_load_lds_dwordx4 v96, s[60:61]
	s_add_u32 m0, s62, 4096
	s_nop 0
	global_load_lds_dwordx4 v97, s[60:61]
	s_add_u32 m0, s62, 8192
	s_nop 0
	global_load_lds_dwordx4 v106, s[60:61]
	s_add_u32 s60, s46, 0x8000
	s_addc_u32 s61, s47, 0
	s_add_u32 m0, s62, 13312
	s_nop 0
	global_load_lds_dwordx4 v213, s[60:61]
	s_add_u32 s60, s60, 0x1000
	s_addc_u32 s61, s61, 0
	s_add_u32 m0, s62, 17408
	s_nop 0
	global_load_lds_dwordx4 v213, s[60:61]
; __device__ __forceinline__ void attn_tile(const u16* sb, const bf16x8 (&qa)[6], f32x16& o0, f32x16& o1, f32x16& lacc,
;                                           float& m, bool& mz, int r, int h, bool first) {
;     ...
;   float mxa = max3f(s0[0], s0[1], s0[2]), mxb = max3f(s0[3], s0[4], s0[5]);
;   float mxc = max3f(s0[6], s0[7], s0[8]), mxd = max3f(s0[9], s0[10], s0[11]);
;   mxa = max3f(mxa, s0[12], s0[13]); mxb = max3f(mxb, s0[14], s0[15]);
;   mxc = max3f(mxc, s1[0], s1[1]); mxd = max3f(mxd, s1[2], s1[3]);
;   mxa = max3f(mxa, s1[4], s1[5]); mxb = max3f(mxb, s1[6], s1[7]);
;   mxc = max3f(mxc, s1[8], s1[9]); mxd = max3f(mxd, s1[10], s1[11]);
;   mxa = max3f(mxa, s1[12], s1[13]); mxb = max3f(mxb, s1[14], s1[15]);
;   const float lm = max3f(mxa, mxb, fmaxf(mxc, mxd));
;   bool slow;
;   if (first) {
;     const float mx = fmaxf(lm, __shfl_xor(lm, 32));
;     slow = __any(mx > 30.f || mx < -30.f);
;   } else {
;     slow = __any(lm > 30.f);
;   }
;   if (slow) {
;     const float mx = fmaxf(lm, __shfl_xor(lm, 32));
;     const float d = first ? mx : fmaxf(mx, 0.f);
;     const float alpha = first ? 1.f : __builtin_amdgcn_exp2f(-d);
;     m += d;
;     mz = false;
; #pragma unroll
;     for (int i = 0; i < 16; ++i) { s0[i] -= d; s1[i] -= d; o0[i] *= alpha; o1[i] *= alpha; }
;     lacc[0] *= alpha;
;   }
.Lvd_skip:
	ds_read_b128 v[214:217], v164 offset:35840
	ds_read_b128 v[218:221], v164 offset:39936
	ds_read_b128 v[222:225], v255 offset:35840
	ds_read_b128 v[226:229], v255 offset:39936
	ds_read_b128 v[230:233], v163 offset:35840
	ds_read_b128 v[234:237], v163 offset:39936
	ds_read_b128 v[238:241], v254 offset:35840
	ds_read_b128 v[242:245], v254 offset:39936
	s_nop 1
	s_setprio 0
	v_max3_f32 v138, v50, v51, v52
	v_max3_f32 v140, v56, v57, v58
	v_max3_f32 v141, v59, v60, v61
	v_max3_f32 v139, v53, v54, v55
	v_max3_f32 v138, v138, v62, v63
	v_max3_f32 v140, v140, v34, v35
	v_max3_f32 v141, v141, v36, v37
	v_max3_f32 v139, v139, v64, v65
	v_max3_f32 v138, v138, v38, v39
	v_max3_f32 v140, v140, v42, v43
	v_max3_f32 v141, v141, v44, v45
	v_max3_f32 v139, v139, v40, v41
	v_max3_f32 v138, v138, v46, v47
	v_max_f32_e32 v141, v141, v141
	v_max_f32_e32 v140, v140, v140
	v_max3_f32 v139, v139, v48, v49
	v_max_f32_e32 v140, v140, v141
	v_max3_f32 v138, v138, v139, v140
	v_cmp_lt_f32_e32 vcc, s5, v138
	s_cbranch_vccz .LBB0_473
	ds_bpermute_b32 v139, v161, v138
	s_andn2_b64 s[50:51], s[48:49], exec
	s_waitcnt lgkmcnt(0)
	v_max3_f32 v138, v138, v139, 0
	v_exp_f32_e64 v140, -v138
	v_add_f32_e32 v162, v162, v138
	v_pk_add_f32 v[50:51], v[50:51], v[138:139] op_sel_hi:[1,0] neg_lo:[0,1] neg_hi:[0,1]
	v_pk_add_f32 v[34:35], v[34:35], v[138:139] op_sel_hi:[1,0] neg_lo:[0,1] neg_hi:[0,1]
	v_pk_add_f32 v[52:53], v[52:53], v[138:139] op_sel_hi:[1,0] neg_lo:[0,1] neg_hi:[0,1]
	v_pk_add_f32 v[36:37], v[36:37], v[138:139] op_sel_hi:[1,0] neg_lo:[0,1] neg_hi:[0,1]
	v_pk_add_f32 v[54:55], v[54:55], v[138:139] op_sel_hi:[1,0] neg_lo:[0,1] neg_hi:[0,1]
	v_pk_add_f32 v[38:39], v[38:39], v[138:139] op_sel_hi:[1,0] neg_lo:[0,1] neg_hi:[0,1]
	v_pk_add_f32 v[56:57], v[56:57], v[138:139] op_sel_hi:[1,0] neg_lo:[0,1] neg_hi:[0,1]
	v_pk_add_f32 v[40:41], v[40:41], v[138:139] op_sel_hi:[1,0] neg_lo:[0,1] neg_hi:[0,1]
	v_pk_add_f32 v[58:59], v[58:59], v[138:139] op_sel_hi:[1,0] neg_lo:[0,1] neg_hi:[0,1]
	v_pk_add_f32 v[42:43], v[42:43], v[138:139] op_sel_hi:[1,0] neg_lo:[0,1] neg_hi:[0,1]
	v_pk_add_f32 v[60:61], v[60:61], v[138:139] op_sel_hi:[1,0] neg_lo:[0,1] neg_hi:[0,1]
	v_pk_add_f32 v[44:45], v[44:45], v[138:139] op_sel_hi:[1,0] neg_lo:[0,1] neg_hi:[0,1]
	v_pk_add_f32 v[62:63], v[62:63], v[138:139] op_sel_hi:[1,0] neg_lo:[0,1] neg_hi:[0,1]
	v_pk_add_f32 v[46:47], v[46:47], v[138:139] op_sel_hi:[1,0] neg_lo:[0,1] neg_hi:[0,1]
	v_pk_add_f32 v[64:65], v[64:65], v[138:139] op_sel_hi:[1,0] neg_lo:[0,1] neg_hi:[0,1]
	v_pk_add_f32 v[48:49], v[48:49], v[138:139] op_sel_hi:[1,0] neg_lo:[0,1] neg_hi:[0,1]
	v_pk_mul_f32 v[32:33], v[32:33], v[140:141] op_sel_hi:[1,0]
	v_pk_mul_f32 v[30:31], v[30:31], v[140:141] op_sel_hi:[1,0]
	v_pk_mul_f32 v[28:29], v[28:29], v[140:141] op_sel_hi:[1,0]
	v_pk_mul_f32 v[26:27], v[26:27], v[140:141] op_sel_hi:[1,0]
	v_pk_mul_f32 v[24:25], v[24:25], v[140:141] op_sel_hi:[1,0]
	v_pk_mul_f32 v[22:23], v[22:23], v[140:141] op_sel_hi:[1,0]
	v_pk_mul_f32 v[20:21], v[20:21], v[140:141] op_sel_hi:[1,0]
	v_pk_mul_f32 v[18:19], v[18:19], v[140:141] op_sel_hi:[1,0]
	v_pk_mul_f32 v[16:17], v[16:17], v[140:141] op_sel_hi:[1,0]
	v_pk_mul_f32 v[14:15], v[14:15], v[140:141] op_sel_hi:[1,0]
	v_pk_mul_f32 v[12:13], v[12:13], v[140:141] op_sel_hi:[1,0]
	v_pk_mul_f32 v[10:11], v[10:11], v[140:141] op_sel_hi:[1,0]
	v_pk_mul_f32 v[8:9], v[8:9], v[140:141] op_sel_hi:[1,0]
	v_pk_mul_f32 v[6:7], v[6:7], v[140:141] op_sel_hi:[1,0]
	v_pk_mul_f32 v[4:5], v[4:5], v[140:141] op_sel_hi:[1,0]
	v_pk_mul_f32 v[2:3], v[2:3], v[140:141] op_sel_hi:[1,0]
	v_mul_f32_e32 v136, v136, v140
	s_branch .LBB0_474
